# meta-token projection of the GEMM1-first workgroups moved into their later weight-conversion pass (memory-bound window)
# baseline (speedup 1.0000x reference)
.LBB0_222:
	s_bitcmp1_b32 s101, 8
	s_cbranch_scc0 .Lcls_222c
	v_readlane_b32 s84, v248, 32
	s_barrier
	s_branch .Lcls_nometa

.LBB0_234:
	v_readfirstlane_b32 s6, v0
	s_cmpk_gt_i32 s84, 0x47f
	s_mov_b64 s[0:1], -1
	s_waitcnt lgkmcnt(0)
	s_barrier
	s_cbranch_scc1 .LBB0_236
	s_ashr_i32 s0, s84, 31
	s_lshr_b32 s0, s0, 29
	s_add_i32 s0, s84, s0
	s_and_b32 s1, s0, -8
	s_sub_i32 s1, s84, s1
	s_cmp_lt_i32 s1, 0
	s_movk_i32 s2, 0x91
	s_cselect_b32 s2, s2, 0x90
	s_mul_i32 s1, s2, s1
	s_ashr_i32 s0, s0, 3
	s_add_i32 s0, s1, s0
	s_ashr_i32 s1, s0, 31
	s_lshr_b32 s1, s1, 24
	s_add_i32 s1, s0, s1
	s_ashr_i32 s1, s1, 8
	s_lshl_b32 s2, s1, 3
	s_sub_i32 s3, 36, s2
	s_lshl_b32 s1, s1, 8
	s_min_u32 s3, s3, 8
	s_sub_i32 s4, s0, s1
	s_sext_i32_i16 s0, s4
	v_cvt_f32_ubyte0_e32 v3, s3
	v_cvt_f32_i32_e32 v2, s0
	v_rcp_iflag_f32_e32 v4, v3
	s_ashr_i32 s0, s0, 30
	s_or_b32 s5, s0, 1
	v_mul_f32_e32 v4, v2, v4
	v_trunc_f32_e32 v4, v4
	v_fma_f32 v2, -v4, v3, v2
	v_cvt_i32_f32_e32 v4, v4
	v_cmp_ge_f32_e64 s[0:1], |v2|, v3
	s_and_b64 s[0:1], s[0:1], exec
	s_cselect_b32 s0, s5, 0
	v_readfirstlane_b32 s1, v4
	s_add_i32 s0, s1, s0
	s_sext_i32_i16 s1, s0
	s_mul_i32 s0, s0, s3
	s_sub_i32 s0, s4, s0
	s_sext_i32_i16 s0, s0
	s_add_i32 s2, s2, s0
	s_lshl_b32 s0, s1, 8
	s_or_b32 s0, s0, s2
	s_mov_b32 s1, 32
.LBB0_236:
	s_bitcmp1_b32 s101, 9
	s_cbranch_scc0 .Lcls_236a
	s_mov_b64 exec, -1
	s_movk_i32 s101, 0x401
	v_readlane_b32 s0, v249, 0
	v_readlane_b32 s1, v249, 1
	v_readlane_b32 s2, v249, 2
	v_mov_b32_e32 v0, v250
	s_nop 4
	s_branch .Lcls_top
.Lcls_236a:
	v_lshlrev_b32_e32 v2, 4, v0
	v_and_b32_e32 v3, 32, v0
	v_bitop3_b32 v171, v2, v3, 48 bitop3:0x6c
	v_lshrrev_b32_e32 v3, 5, v0
	v_lshrrev_b32_e32 v5, 1, v0
	v_or_b32_e32 v174, 0x2000, v2
	v_bfe_u32 v173, v0, 2, 4
	v_and_b32_e32 v3, 4, v3
	v_bfe_u32 v4, v0, 2, 2
	v_and_b32_e32 v175, 24, v5
	v_lshrrev_b32_e32 v2, 7, v174
	s_movk_i32 s2, 0x70
	v_or3_b32 v3, v3, v4, v175
	v_and_or_b32 v180, v2, s2, v173
	s_movk_i32 s2, 0x60
	v_and_or_b32 v181, v2, s2, v3
	v_lshlrev_b32_e32 v2, 6, v0
	v_and_b32_e32 v172, 64, v0
	v_lshrrev_b32_e32 v4, 3, v0
	v_lshlrev_b32_e32 v176, 1, v175
	v_and_b32_e32 v2, 0x3c0, v2
	v_and_b32_e32 v1, 32, v1
	v_cmp_lt_i64_e64 s[2:3], s[0:1], 0
	v_or_b32_e32 v177, v171, v172
	v_and_or_b32 v178, v4, 48, v173
	v_and_or_b32 v179, v4, 32, v3
	v_bitop3_b32 v1, v176, v1, v2 bitop3:0x36
	s_and_b64 vcc, exec, s[2:3]
	s_cbranch_vccnz .LBB0_256
	s_lshr_b32 s2, s0, 13
	s_lshr_b32 s10, s6, 6
	s_and_b32 s8, s2, 0x7ff80
	s_lshl_b32 s2, s0, 20
	s_lshr_b32 s7, s6, 8
	s_lshl_b32 s16, s10, 10
	s_bfe_u32 s33, s0, 0x80008
	s_and_b32 s2, s2, 0xff00000
	v_readlane_b32 s4, v248, 22
	v_readlane_b32 s5, v248, 23
	s_add_u32 s9, s4, s2
	s_addc_u32 s11, s5, 0
	s_lshl_b32 s2, s33, 20
	v_readlane_b32 s4, v248, 24
	v_readlane_b32 s5, v248, 25
	s_add_u32 s2, s4, s2
	s_addc_u32 s3, s5, 0
	s_add_u32 s2, s2, s8
	s_addc_u32 s3, s3, 0
	s_add_i32 s17, s16, 0
	v_lshl_or_b32 v132, v179, 12, v177
	s_add_i32 m0, s17, 0x10000
	v_lshl_or_b32 v136, v181, 12, v177
	global_load_lds_dwordx4 v132, s[2:3]
	s_add_i32 m0, s17, 0x12000
	s_add_u32 s4, s2, 0x80000
	global_load_lds_dwordx4 v136, s[2:3]
	s_addc_u32 s5, s3, 0
	s_add_i32 m0, s17, 0x14000
	v_lshl_or_b32 v130, v178, 12, v177
	global_load_lds_dwordx4 v132, s[4:5]
	s_add_i32 m0, s17, 0x16000
	v_lshl_or_b32 v134, v180, 12, v177
	global_load_lds_dwordx4 v136, s[4:5]
	s_add_u32 s4, s9, s8
	s_addc_u32 s5, s11, 0
	s_add_i32 s18, s17, 0x2000
	s_mov_b32 m0, s17
	s_add_u32 s8, s4, 0x80000
	global_load_lds_dwordx4 v130, s[4:5]
	s_mov_b32 m0, s18
	s_addc_u32 s9, s5, 0
	s_add_i32 s19, s17, 0x4000
	global_load_lds_dwordx4 v134, s[4:5]
	s_mov_b32 m0, s19
	s_add_i32 s20, s17, 0x6000
	global_load_lds_dwordx4 v130, s[8:9]
	s_mov_b32 m0, s20
	v_mov_b32_e32 v139, 0
	global_load_lds_dwordx4 v134, s[8:9]
	v_mov_b32_e32 v133, v139
	v_mov_b32_e32 v137, v139
	v_mov_b32_e32 v131, v139
	v_mov_b32_e32 v135, v139
	s_cmp_eq_u32 s7, 1
	s_mov_b32 s21, 0
	v_lshl_add_u64 v[8:9], s[2:3], 0, v[132:133]
	v_lshl_add_u64 v[6:7], s[2:3], 0, v[136:137]
	v_lshl_add_u64 v[2:3], s[4:5], 0, v[130:131]
	s_cselect_b64 s[8:9], -1, 0
	s_cmp_lg_u32 s7, 1
	v_lshl_add_u64 v[4:5], s[4:5], 0, v[134:135]
	s_cbranch_scc1 .LBB0_239
	s_barrier
